# up-projection phase start: waves 4-7 warm L2 with the first weight k-steps before the row-panel gate
# baseline (speedup 1.0000x reference)
.LBB0_333:
	v_readfirstlane_b32 s101, v234
	s_cmpk_lt_u32 s101, 0x100
	s_cbranch_scc1 .Lsw_pf_skip
	v_readlane_b32 s100, v254, 47
	s_nop 0
	s_lshr_b32 s100, s100, 6
	s_lshl_b32 s100, s100, 19
	s_cmp_eq_u32 s74, 13
	s_mov_b32 s101, 0x5180000
	s_cselect_b32 s101, 0x1900000, s101
	s_add_u32 s100, s100, s101
	s_add_u32 s100, s0, s100
	s_addc_u32 s101, s1, 0
	v_lshlrev_b32_e32 v252, 11, v234
	v_add_u32_e32 v252, 0xfff80000, v252
	global_load_dword v253, v252, s[100:101]
	global_load_dword v253, v252, s[100:101] offset:64
	global_load_dword v253, v252, s[100:101] offset:128
	global_load_dword v253, v252, s[100:101] offset:192

.LBB0_352:
	s_waitcnt vmcnt(0)
.LBB0_353:
	s_or_b64 exec, exec, s[6:7]
	s_barrier
.LBB0_354:
	v_readlane_b32 s6, v254, 47
	s_cmpk_gt_i32 s6, 0x57f
	v_readfirstlane_b32 s16, v234
	v_readlane_b32 s7, v254, 48
	s_cbranch_scc1 .LBB0_386
	v_lshlrev_b32_e32 v2, 4, v234
	v_add_u32_e32 v3, 0x2000, v2
	v_ashrrev_i32_e32 v4, 31, v3
	v_lshrrev_b32_e32 v4, 22, v4
	v_add_u32_e32 v4, v3, v4
	v_ashrrev_i32_e32 v10, 10, v4
	v_mul_i32_i24_e32 v4, 0x400, v10
	v_sub_u32_e32 v3, v3, v4
	v_lshrrev_b32_e32 v4, 4, v3
	v_bitop3_b32 v3, v4, v3, 32 bitop3:0x6c
	s_ashr_i32 s17, s16, 6
	v_ashrrev_i32_e32 v4, 31, v3
	s_ashr_i32 s18, s16, 8
	s_lshl_b32 s44, s17, 10
	v_lshrrev_b32_e32 v4, 26, v4
	s_and_b64 s[6:7], s[4:5], exec
	v_add_u32_e32 v4, v3, v4
	v_lshlrev_b32_e32 v5, 3, v10
	s_mov_b32 s6, 0x1900000
	v_ashrrev_i32_e32 v12, 6, v4
	v_and_b32_e32 v5, -16, v5
	s_cselect_b32 s6, s6, 0x5180000
	v_add_u32_e32 v5, v12, v5
	s_add_u32 s45, s0, s6
	v_and_b32_e32 v6, 3, v12
	s_mov_b32 s6, 0x1fffe0
	v_lshrrev_b32_e32 v7, 2, v5
	v_lshlrev_b32_e32 v8, 1, v5
	v_and_b32_e32 v4, 0xc0, v4
	v_and_or_b32 v6, v5, s6, v6
	v_and_b32_e32 v7, 4, v7
	v_and_b32_e32 v8, 24, v8
	v_sub_u32_e32 v3, v3, v4
	v_or3_b32 v6, v6, v7, v8
	v_lshlrev_b32_e32 v7, 5, v10
	v_ashrrev_i16_sdwa v3, v226, sext(v3) dst_sel:DWORD dst_unused:UNUSED_PAD src0_sel:DWORD src1_sel:BYTE_0
	v_and_b32_e32 v7, 32, v7
	v_bfe_i32 v13, v3, 0, 16
	v_add_lshl_u32 v3, v7, v13, 1
	s_waitcnt vmcnt(0)
	v_lshl_add_u32 v130, v6, 11, v3
	v_lshl_add_u32 v132, v5, 11, v3
	v_bfe_i32 v3, v234, 27, 1
	v_lshrrev_b32_e32 v3, 22, v3
	v_add_u32_e32 v3, v2, v3
	v_and_b32_e32 v3, 0xfffffc00, v3
	v_sub_u32_e32 v2, v2, v3
	v_lshrrev_b32_e32 v3, 4, v2
	v_ashrrev_i32_e32 v4, 31, v234
	s_addc_u32 s46, s1, 0
	v_bitop3_b32 v2, v3, v2, 32 bitop3:0x6c
	v_lshrrev_b32_e32 v4, 26, v4
	v_ashrrev_i32_e32 v3, 31, v2
	v_add_u32_e32 v4, v234, v4
	s_and_b64 s[4:5], s[4:5], exec
	v_lshrrev_b32_e32 v3, 26, v3
	v_ashrrev_i32_e32 v15, 6, v4
	s_mov_b32 s4, 0x30000
	v_add_u32_e32 v3, v2, v3
	v_lshlrev_b32_e32 v4, 3, v15
	s_cselect_b32 s4, s4, 0x10000
	v_ashrrev_i32_e32 v14, 6, v3
	v_and_b32_e32 v4, -16, v4
	s_add_u32 s12, s78, s4
	v_readlane_b32 s4, v254, 47
	v_add_u32_e32 v4, v14, v4
	v_and_b32_e32 v5, 3, v14
	s_addc_u32 s13, s79, 0
	s_ashr_i32 s47, s4, 31
	v_and_or_b32 v5, v4, s6, v5
	s_mov_b32 s6, s4
	s_lshr_b32 s4, s47, 29
	v_readlane_b32 s5, v254, 48
	s_add_i32 s4, s6, s4
	s_ashr_i32 s5, s4, 3
	s_and_b32 s4, s4, -8
	s_sub_i32 s4, s6, s4
	s_cmp_lt_i32 s4, 0
	s_movk_i32 s6, 0xb1
	s_cselect_b32 s6, s6, 0xb0
	s_mul_i32 s4, s4, s6
	s_add_i32 s4, s4, s5
	s_mul_hi_i32 s5, s4, 0x2e8ba2e9
	s_lshr_b32 s6, s5, 31
	s_ashr_i32 s5, s5, 5
	s_add_i32 s5, s5, s6
	s_lshl_b32 s6, s5, 3
	s_mulk_i32 s5, 0xb0
	s_sub_i32 s5, s4, s5
	s_bfe_u32 s4, s5, 0x3001c
	s_add_i32 s7, s5, s4
	s_sext_i32_i16 s4, s7
	s_and_b32 s7, s7, 0xfff8
	s_sub_i32 s5, s5, s7
	s_sext_i32_i16 s5, s5
	v_lshrrev_b32_e32 v6, 2, v4
	v_lshlrev_b32_e32 v7, 1, v4
	v_and_b32_e32 v3, 0xc0, v3
	s_lshr_b32 s4, s4, 3
	s_add_i32 s28, s6, s5
	v_and_b32_e32 v6, 4, v6
	v_and_b32_e32 v7, 24, v7
	v_sub_u32_e32 v2, v2, v3
	s_ashr_i32 s29, s28, 31
	s_bfe_i64 s[14:15], s[4:5], 0x100000
	v_or3_b32 v5, v5, v6, v7
	v_lshlrev_b32_e32 v6, 5, v15
	v_ashrrev_i16_sdwa v2, v226, sext(v2) dst_sel:DWORD dst_unused:UNUSED_PAD src0_sel:DWORD src1_sel:BYTE_0
	s_lshl_b64 s[6:7], s[28:29], 19
	s_lshl_b64 s[14:15], s[14:15], 19
	v_and_b32_e32 v11, 15, v233
	v_and_b32_e32 v6, 32, v6
	v_bfe_i32 v16, v2, 0, 16
	s_add_u32 s30, s45, s14
	v_lshl_or_b32 v1, s18, 6, v11
	v_add_lshl_u32 v2, v6, v16, 1
	s_addc_u32 s31, s46, s15
	s_lshl_b32 s5, s28, 8
	v_lshl_add_u32 v134, v5, 11, v2
	v_lshl_add_u32 v136, v4, 11, v2
	v_add_u32_e32 v2, s5, v1
	v_ashrrev_i32_e32 v3, 31, v2
	v_lshl_add_u64 v[2:3], v[2:3], 2, s[12:13]
	v_or_b32_e32 v148, 16, v1
	global_load_dword v166, v[2:3], off
	v_add_u32_e32 v2, s5, v148
	v_ashrrev_i32_e32 v3, 31, v2
	v_lshl_add_u64 v[2:3], v[2:3], 2, s[12:13]
	v_or_b32_e32 v149, 32, v1
	global_load_dword v165, v[2:3], off
	v_add_u32_e32 v2, s5, v149
	v_ashrrev_i32_e32 v3, 31, v2
	v_lshl_add_u64 v[2:3], v[2:3], 2, s[12:13]
	v_or_b32_e32 v150, 48, v1
	global_load_dword v163, v[2:3], off
	v_add_u32_e32 v2, s5, v150
	v_ashrrev_i32_e32 v3, 31, v2
	v_lshl_add_u64 v[2:3], v[2:3], 2, s[12:13]
	v_add_u32_e32 v151, 0x80, v1
	global_load_dword v162, v[2:3], off
	v_add_u32_e32 v2, s5, v151
	v_ashrrev_i32_e32 v3, 31, v2
	s_add_i32 s48, s44, 0
	v_lshl_add_u64 v[2:3], v[2:3], 2, s[12:13]
	v_add_u32_e32 v152, 0x90, v1
	s_add_i32 m0, s48, 0x10000
	global_load_dword v161, v[2:3], off
	v_add_u32_e32 v2, s5, v152
	global_load_lds_dwordx4 v134, s[30:31]
	s_add_i32 m0, s48, 0x12000
	v_ashrrev_i32_e32 v3, 31, v2
	s_add_u32 s14, s30, 0x40000
	v_lshl_add_u64 v[2:3], v[2:3], 2, s[12:13]
	v_add_u32_e32 v153, 0xa0, v1
	global_load_lds_dwordx4 v130, s[30:31]
	s_addc_u32 s15, s31, 0
	s_add_i32 m0, s48, 0x14000
	global_load_dword v160, v[2:3], off
	v_add_u32_e32 v2, s5, v153
	global_load_lds_dwordx4 v134, s[14:15]
	s_add_i32 m0, s48, 0x16000
	v_ashrrev_i32_e32 v3, 31, v2
	s_add_u32 s34, s80, s6
	v_lshl_add_u64 v[2:3], v[2:3], 2, s[12:13]
	v_add_u32_e32 v154, 0xb0, v1
	s_addc_u32 s35, s81, s7
	s_add_i32 s49, s48, 0x2000
	global_load_dword v159, v[2:3], off
	v_add_u32_e32 v2, s5, v154
	global_load_lds_dwordx4 v130, s[14:15]
	s_mov_b32 m0, s48
	s_add_u32 s6, s34, 0x40000
	v_ashrrev_i32_e32 v3, 31, v2
	global_load_lds_dwordx4 v136, s[34:35]
	s_mov_b32 m0, s49
	s_addc_u32 s7, s35, 0
	s_add_i32 s50, s48, 0x4000
	v_lshl_add_u64 v[2:3], v[2:3], 2, s[12:13]
	global_load_lds_dwordx4 v132, s[34:35]
	s_mov_b32 m0, s50
	s_add_i32 s51, s48, 0x6000
	global_load_dword v158, v[2:3], off
	v_mov_b32_e32 v135, v0
	global_load_lds_dwordx4 v136, s[6:7]
	s_mov_b32 m0, s51
	v_mov_b32_e32 v131, v0
	global_load_lds_dwordx4 v132, s[6:7]
	v_mov_b32_e32 v137, v0
	v_mov_b32_e32 v133, v0
	s_cmp_eq_u32 s18, 1
	v_lshl_add_u64 v[2:3], s[30:31], 0, v[134:135]
	v_lshl_add_u64 v[4:5], s[30:31], 0, v[130:131]
	v_lshl_add_u64 v[6:7], s[34:35], 0, v[136:137]
	v_lshl_add_u64 v[8:9], s[34:35], 0, v[132:133]
	s_cselect_b64 s[14:15], -1, 0
	s_cmp_lg_u32 s18, 1
	s_cbranch_scc1 .LBB0_357
	s_barrier
